# wo-GEMM (phase 8) epilogue: 8-byte stores widened to 16-byte with v_permlane16_swap, vmcnt waits re-derived
# speedup vs baseline: 1.0184x; 1.0092x over previous
.LBB0_538:
	v_mbcnt_lo_u32_b32 v234, -1, 0
	v_mbcnt_hi_u32_b32 v234, -1, v234
	v_and_b32_e32 v234, 16, v234
	v_mul_u32_u24_e32 v234, 3, v234
	v_lshrrev_b32_e32 v234, 1, v234
	v_mov_b32_e32 v235, 0
	v_lshl_add_u32 v172, s22, 8, v187
	v_ashrrev_i32_e32 v173, 31, v172
	v_lshl_add_u64 v[82:83], v[172:173], 3, s[4:5]
	v_lshl_or_b32 v80, s43, 8, v191
	global_load_dwordx2 v[180:181], v[82:83], off
	v_ashrrev_i32_e32 v81, 31, v80
	v_lshlrev_b64 v[82:83], 11, v[172:173]
	v_lshl_add_u64 v[82:83], s[88:89], 0, v[82:83]
	v_lshlrev_b64 v[174:175], 1, v[80:81]
	v_lshl_add_u64 v[178:179], v[82:83], 0, v[174:175]
	global_load_dwordx2 v[182:183], v[178:179], off
	global_load_dwordx2 v[196:197], v[178:179], off offset:32
	global_load_dwordx2 v[198:199], v[178:179], off offset:256
	global_load_dwordx2 v[200:201], v[178:179], off offset:288
	v_lshlrev_b64 v[80:81], 2, v[80:81]
	v_lshl_add_u64 v[92:93], s[72:73], 0, v[80:81]
	v_lshl_add_u64 v[108:109], s[74:75], 0, v[80:81]
	global_load_dwordx4 v[80:83], v[108:109], off
	global_load_dwordx4 v[96:99], v[92:93], off
	global_load_dwordx4 v[84:87], v[92:93], off offset:64
	global_load_dwordx4 v[100:103], v[108:109], off offset:64
	global_load_dwordx4 v[88:91], v[108:109], off offset:512
	global_load_dwordx4 v[104:107], v[92:93], off offset:512
	s_nop 0
	global_load_dwordx4 v[92:95], v[92:93], off offset:576
	s_nop 0
	global_load_dwordx4 v[108:111], v[108:109], off offset:576
	v_or_b32_e32 v202, 16, v172
	v_or_b32_e32 v204, 32, v172
	v_ashrrev_i32_e32 v203, 31, v202
	v_ashrrev_i32_e32 v205, 31, v204
	v_lshlrev_b64 v[176:177], 11, v[202:203]
	v_lshlrev_b64 v[188:189], 11, v[204:205]
	v_lshl_add_u64 v[176:177], s[88:89], 0, v[176:177]
	v_lshl_add_u64 v[188:189], s[88:89], 0, v[188:189]
	v_lshl_add_u64 v[206:207], v[176:177], 0, v[174:175]
	v_lshl_add_u64 v[176:177], v[188:189], 0, v[174:175]
	global_load_dwordx2 v[208:209], v[206:207], off
	global_load_dwordx2 v[210:211], v[206:207], off offset:256
	global_load_dwordx2 v[188:189], v[176:177], off
	s_andn2_b64 vcc, exec, s[2:3]
	s_mov_b64 s[2:3], -1
	s_waitcnt vmcnt(0)
	v_pk_mul_f32 v[180:181], v[180:181], s[10:11] op_sel_hi:[1,0]
	s_nop 0
	v_fma_f32 v173, -v180, v180, v181
	v_max_f32_e32 v173, 0, v173
	v_add_f32_e32 v173, 0x3727c5ac, v173
	v_lshlrev_b32_e32 v181, 16, v182
	v_and_b32_e32 v182, 0xffff0000, v182
	v_lshlrev_b32_e32 v221, 16, v200
	v_and_b32_e32 v222, 0xffff0000, v200
	v_rsq_f32_e32 v200, v173
	v_lshlrev_b32_e32 v195, 16, v183
	v_and_b32_e32 v212, 0xffff0000, v183
	v_lshlrev_b32_e32 v213, 16, v196
	v_and_b32_e32 v214, 0xffff0000, v196
	v_lshlrev_b32_e32 v215, 16, v197
	v_and_b32_e32 v216, 0xffff0000, v197
	v_lshlrev_b32_e32 v217, 16, v198
	v_and_b32_e32 v218, 0xffff0000, v198
	v_lshlrev_b32_e32 v219, 16, v199
	v_and_b32_e32 v220, 0xffff0000, v199
	v_sub_f32_e32 v183, v182, v180
	v_sub_f32_e32 v182, v181, v180
	v_sub_f32_e32 v197, v212, v180
	v_sub_f32_e32 v196, v195, v180
	v_sub_f32_e32 v199, v214, v180
	v_sub_f32_e32 v198, v213, v180
	v_sub_f32_e32 v213, v216, v180
	v_sub_f32_e32 v212, v215, v180
	v_sub_f32_e32 v215, v218, v180
	v_sub_f32_e32 v214, v217, v180
	v_sub_f32_e32 v217, v220, v180
	v_sub_f32_e32 v216, v219, v180
	v_pk_mul_f32 v[196:197], v[200:201], v[196:197] op_sel_hi:[0,1]
	v_pk_mul_f32 v[182:183], v[200:201], v[182:183] op_sel_hi:[0,1]
	v_pk_mul_f32 v[216:217], v[200:201], v[216:217] op_sel_hi:[0,1]
	v_pk_mul_f32 v[214:215], v[200:201], v[214:215] op_sel_hi:[0,1]
	v_pk_mul_f32 v[212:213], v[200:201], v[212:213] op_sel_hi:[0,1]
	v_pk_mul_f32 v[198:199], v[200:201], v[198:199] op_sel_hi:[0,1]
	v_pk_fma_f32 v[182:183], v[96:97], v[182:183], v[80:81]
	v_pk_fma_f32 v[196:197], v[98:99], v[196:197], v[82:83]
	v_pk_fma_f32 v[214:215], v[104:105], v[214:215], v[88:89]
	v_pk_fma_f32 v[216:217], v[106:107], v[216:217], v[90:91]
	v_pk_fma_f32 v[198:199], v[84:85], v[198:199], v[100:101]
	v_pk_fma_f32 v[212:213], v[86:87], v[212:213], v[102:103]
	v_pk_fma_f32 v[158:159], v[196:197], s[12:13], v[158:159] op_sel_hi:[1,0,1]
	v_pk_fma_f32 v[156:157], v[182:183], s[12:13], v[156:157] op_sel_hi:[1,0,1]
	v_pk_fma_f32 v[150:151], v[216:217], s[12:13], v[150:151] op_sel_hi:[1,0,1]
	v_pk_fma_f32 v[148:149], v[214:215], s[12:13], v[148:149] op_sel_hi:[1,0,1]
	v_pk_fma_f32 v[154:155], v[212:213], s[12:13], v[154:155] op_sel_hi:[1,0,1]
	v_pk_fma_f32 v[152:153], v[198:199], s[12:13], v[152:153] op_sel_hi:[1,0,1]
	v_cvt_pk_bf16_f32 v156, v156, v157
	v_cvt_pk_bf16_f32 v157, v158, v159
	v_cvt_pk_bf16_f32 v148, v148, v149
	v_cvt_pk_bf16_f32 v149, v150, v151
	v_lshlrev_b32_e32 v150, 16, v201
	v_and_b32_e32 v151, 0xffff0000, v201
	v_cvt_pk_bf16_f32 v152, v152, v153
	v_cvt_pk_bf16_f32 v153, v154, v155
	v_mov_b32_e32 v224, v156
	v_mov_b32_e32 v225, v157
	v_mov_b32_e32 v226, v152
	v_mov_b32_e32 v227, v153
	v_lshl_add_u64 v[232:233], v[178:179], 0, v[234:235]
	s_nop 0
	v_permlane16_swap_b32 v224, v226
	v_permlane16_swap_b32 v225, v227
	global_store_dwordx4 v[232:233], v[224:227], off
	v_mov_b32_e32 v228, v148
	v_mov_b32_e32 v229, v149
	v_sub_f32_e32 v149, v222, v180
	v_sub_f32_e32 v148, v221, v180
	v_sub_f32_e32 v151, v151, v180
	v_sub_f32_e32 v150, v150, v180
	v_pk_mul_f32 v[150:151], v[200:201], v[150:151] op_sel_hi:[0,1]
	v_pk_mul_f32 v[148:149], v[200:201], v[148:149] op_sel_hi:[0,1]
	v_pk_fma_f32 v[148:149], v[92:93], v[148:149], v[108:109]
	v_pk_fma_f32 v[150:151], v[94:95], v[150:151], v[110:111]
	v_pk_fma_f32 v[144:145], v[148:149], s[12:13], v[144:145] op_sel_hi:[1,0,1]
	v_pk_fma_f32 v[146:147], v[150:151], s[12:13], v[146:147] op_sel_hi:[1,0,1]
	v_cvt_pk_bf16_f32 v144, v144, v145
	v_cvt_pk_bf16_f32 v145, v146, v147
	v_mov_b32_e32 v230, v144
	v_mov_b32_e32 v231, v145
	s_nop 1
	v_permlane16_swap_b32 v228, v230
	v_permlane16_swap_b32 v229, v231
	global_store_dwordx4 v[232:233], v[228:231], off offset:256
	v_lshl_add_u64 v[144:145], v[202:203], 3, s[4:5]
	global_load_dwordx2 v[144:145], v[144:145], off
	s_nop 0
	global_load_dwordx2 v[146:147], v[206:207], off offset:32
	global_load_dwordx2 v[148:149], v[206:207], off offset:288
	v_and_b32_e32 v155, 0xffff0000, v209
	v_lshlrev_b32_e32 v152, 16, v208
	v_and_b32_e32 v153, 0xffff0000, v208
	v_lshlrev_b32_e32 v154, 16, v209
	v_lshlrev_b32_e32 v156, 16, v210
	v_and_b32_e32 v157, 0xffff0000, v210
	v_lshlrev_b32_e32 v158, 16, v211
	v_and_b32_e32 v159, 0xffff0000, v211
	global_load_dwordx2 v[150:151], v[176:177], off offset:32
	s_waitcnt vmcnt(3)
	v_pk_mul_f32 v[144:145], v[144:145], s[10:11] op_sel_hi:[1,0]
	s_nop 0
	v_fma_f32 v145, -v144, v144, v145
	v_max_f32_e32 v145, 0, v145
	s_waitcnt vmcnt(2)
	v_and_b32_e32 v180, 0xffff0000, v147
	v_add_f32_e32 v145, 0x3727c5ac, v145
	s_waitcnt vmcnt(1)
	v_lshlrev_b32_e32 v183, 16, v149
	v_and_b32_e32 v195, 0xffff0000, v149
	v_sub_f32_e32 v149, v155, v144
	v_sub_f32_e32 v155, v180, v144
	v_rsq_f32_e32 v180, v145
	v_lshlrev_b32_e32 v173, 16, v146
	v_and_b32_e32 v178, 0xffff0000, v146
	v_lshlrev_b32_e32 v179, 16, v147
	v_lshlrev_b32_e32 v181, 16, v148
	v_and_b32_e32 v182, 0xffff0000, v148
	v_sub_f32_e32 v147, v153, v144
	v_sub_f32_e32 v146, v152, v144
	v_sub_f32_e32 v148, v154, v144
	v_sub_f32_e32 v153, v178, v144
	v_sub_f32_e32 v152, v173, v144
	v_sub_f32_e32 v154, v179, v144
	v_sub_f32_e32 v157, v157, v144
	v_sub_f32_e32 v156, v156, v144
	v_sub_f32_e32 v159, v159, v144
	v_sub_f32_e32 v158, v158, v144
	v_sub_f32_e32 v179, v182, v144
	v_sub_f32_e32 v178, v181, v144
	v_sub_f32_e32 v145, v195, v144
	v_sub_f32_e32 v144, v183, v144
	v_pk_mul_f32 v[148:149], v[180:181], v[148:149] op_sel_hi:[0,1]
	v_pk_mul_f32 v[146:147], v[180:181], v[146:147] op_sel_hi:[0,1]
	v_pk_mul_f32 v[144:145], v[180:181], v[144:145] op_sel_hi:[0,1]
	v_pk_mul_f32 v[178:179], v[180:181], v[178:179] op_sel_hi:[0,1]
	v_pk_mul_f32 v[154:155], v[180:181], v[154:155] op_sel_hi:[0,1]
	v_pk_mul_f32 v[152:153], v[180:181], v[152:153] op_sel_hi:[0,1]
	v_pk_mul_f32 v[158:159], v[180:181], v[158:159] op_sel_hi:[0,1]
	v_pk_mul_f32 v[156:157], v[180:181], v[156:157] op_sel_hi:[0,1]
	v_pk_fma_f32 v[146:147], v[96:97], v[146:147], v[80:81]
	v_pk_fma_f32 v[148:149], v[98:99], v[148:149], v[82:83]
	v_pk_fma_f32 v[178:179], v[92:93], v[178:179], v[108:109]
	v_pk_fma_f32 v[144:145], v[94:95], v[144:145], v[110:111]
	v_pk_fma_f32 v[152:153], v[84:85], v[152:153], v[100:101]
	v_pk_fma_f32 v[154:155], v[86:87], v[154:155], v[102:103]
	v_pk_fma_f32 v[156:157], v[104:105], v[156:157], v[88:89]
	v_pk_fma_f32 v[158:159], v[106:107], v[158:159], v[90:91]
	v_pk_fma_f32 v[142:143], v[148:149], s[12:13], v[142:143] op_sel_hi:[1,0,1]
	v_pk_fma_f32 v[140:141], v[146:147], s[12:13], v[140:141] op_sel_hi:[1,0,1]
	v_pk_fma_f32 v[130:131], v[144:145], s[12:13], v[130:131] op_sel_hi:[1,0,1]
	v_pk_fma_f32 v[128:129], v[178:179], s[12:13], v[128:129] op_sel_hi:[1,0,1]
	v_pk_fma_f32 v[138:139], v[154:155], s[12:13], v[138:139] op_sel_hi:[1,0,1]
	v_pk_fma_f32 v[136:137], v[152:153], s[12:13], v[136:137] op_sel_hi:[1,0,1]
	v_pk_fma_f32 v[134:135], v[158:159], s[12:13], v[134:135] op_sel_hi:[1,0,1]
	v_pk_fma_f32 v[132:133], v[156:157], s[12:13], v[132:133] op_sel_hi:[1,0,1]
	v_cvt_pk_bf16_f32 v140, v140, v141
	v_cvt_pk_bf16_f32 v141, v142, v143
	v_cvt_pk_bf16_f32 v128, v128, v129
	v_cvt_pk_bf16_f32 v129, v130, v131
	v_cvt_pk_bf16_f32 v136, v136, v137
	v_cvt_pk_bf16_f32 v137, v138, v139
	v_cvt_pk_bf16_f32 v132, v132, v133
	v_cvt_pk_bf16_f32 v133, v134, v135
	v_mov_b32_e32 v224, v140
	v_mov_b32_e32 v225, v141
	v_mov_b32_e32 v226, v136
	v_mov_b32_e32 v227, v137
	v_lshl_add_u64 v[232:233], v[206:207], 0, v[234:235]
	s_nop 0
	v_permlane16_swap_b32 v224, v226
	v_permlane16_swap_b32 v225, v227
	global_store_dwordx4 v[232:233], v[224:227], off
	v_mov_b32_e32 v228, v132
	v_mov_b32_e32 v229, v133
	v_mov_b32_e32 v230, v128
	v_mov_b32_e32 v231, v129
	s_nop 1
	v_permlane16_swap_b32 v228, v230
	v_permlane16_swap_b32 v229, v231
	global_store_dwordx4 v[232:233], v[228:231], off offset:256
	v_lshl_add_u64 v[128:129], v[204:205], 3, s[4:5]
	global_load_dwordx2 v[132:133], v[128:129], off
	global_load_dwordx2 v[134:135], v[176:177], off offset:256
	global_load_dwordx2 v[136:137], v[176:177], off offset:288
	v_lshlrev_b32_e32 v142, 16, v189
	s_waitcnt vmcnt(5)
	v_lshlrev_b32_e32 v144, 16, v150
	v_and_b32_e32 v145, 0xffff0000, v150
	v_lshlrev_b32_e32 v146, 16, v151
	v_lshlrev_b32_e32 v140, 16, v188
	v_and_b32_e32 v141, 0xffff0000, v188
	v_and_b32_e32 v143, 0xffff0000, v189
	v_or_b32_e32 v128, 48, v172
	v_and_b32_e32 v147, 0xffff0000, v151
	v_ashrrev_i32_e32 v129, 31, v128
	v_lshl_add_u64 v[138:139], v[128:129], 3, s[4:5]
	v_lshlrev_b64 v[128:129], 11, v[128:129]
	v_lshl_add_u64 v[128:129], s[88:89], 0, v[128:129]
	v_lshl_add_u64 v[128:129], v[128:129], 0, v[174:175]
	global_load_dwordx2 v[130:131], v[128:129], off
	s_waitcnt vmcnt(3)
	v_pk_mul_f32 v[132:133], v[132:133], s[10:11] op_sel_hi:[1,0]
	s_nop 0
	v_fma_f32 v133, -v132, v132, v133
	v_max_f32_e32 v133, 0, v133
	s_waitcnt vmcnt(2)
	v_lshlrev_b32_e32 v150, 16, v135
	v_add_f32_e32 v133, 0x3727c5ac, v133
	s_waitcnt vmcnt(1)
	v_lshlrev_b32_e32 v152, 16, v136
	v_and_b32_e32 v153, 0xffff0000, v136
	v_sub_f32_e32 v136, v142, v132
	v_sub_f32_e32 v142, v146, v132
	v_sub_f32_e32 v146, v150, v132
	v_rsq_f32_e32 v150, v133
	v_lshlrev_b32_e32 v148, 16, v134
	v_and_b32_e32 v149, 0xffff0000, v134
	v_and_b32_e32 v151, 0xffff0000, v135
	v_lshlrev_b32_e32 v154, 16, v137
	v_and_b32_e32 v155, 0xffff0000, v137
	v_sub_f32_e32 v135, v141, v132
	v_sub_f32_e32 v134, v140, v132
	v_sub_f32_e32 v137, v143, v132
	v_sub_f32_e32 v141, v145, v132
	v_sub_f32_e32 v140, v144, v132
	v_sub_f32_e32 v143, v147, v132
	v_sub_f32_e32 v145, v149, v132
	v_sub_f32_e32 v144, v148, v132
	v_sub_f32_e32 v147, v151, v132
	v_sub_f32_e32 v149, v153, v132
	v_sub_f32_e32 v148, v152, v132
	v_sub_f32_e32 v133, v155, v132
	v_sub_f32_e32 v132, v154, v132
	v_pk_mul_f32 v[136:137], v[150:151], v[136:137] op_sel_hi:[0,1]
	v_pk_mul_f32 v[134:135], v[150:151], v[134:135] op_sel_hi:[0,1]
	v_pk_mul_f32 v[142:143], v[150:151], v[142:143] op_sel_hi:[0,1]
	v_pk_mul_f32 v[140:141], v[150:151], v[140:141] op_sel_hi:[0,1]
	v_pk_mul_f32 v[146:147], v[150:151], v[146:147] op_sel_hi:[0,1]
	v_pk_mul_f32 v[144:145], v[150:151], v[144:145] op_sel_hi:[0,1]
	v_pk_mul_f32 v[132:133], v[150:151], v[132:133] op_sel_hi:[0,1]
	v_pk_mul_f32 v[148:149], v[150:151], v[148:149] op_sel_hi:[0,1]
	v_pk_fma_f32 v[134:135], v[96:97], v[134:135], v[80:81]
	v_pk_fma_f32 v[136:137], v[98:99], v[136:137], v[82:83]
	v_pk_fma_f32 v[140:141], v[84:85], v[140:141], v[100:101]
	v_pk_fma_f32 v[142:143], v[86:87], v[142:143], v[102:103]
	v_pk_fma_f32 v[144:145], v[104:105], v[144:145], v[88:89]
	v_pk_fma_f32 v[146:147], v[106:107], v[146:147], v[90:91]
	v_pk_fma_f32 v[148:149], v[92:93], v[148:149], v[108:109]
	v_pk_fma_f32 v[132:133], v[94:95], v[132:133], v[110:111]
	v_pk_fma_f32 v[126:127], v[136:137], s[12:13], v[126:127] op_sel_hi:[1,0,1]
	v_pk_fma_f32 v[124:125], v[134:135], s[12:13], v[124:125] op_sel_hi:[1,0,1]
	v_pk_fma_f32 v[122:123], v[142:143], s[12:13], v[122:123] op_sel_hi:[1,0,1]
	v_pk_fma_f32 v[120:121], v[140:141], s[12:13], v[120:121] op_sel_hi:[1,0,1]
	v_pk_fma_f32 v[118:119], v[146:147], s[12:13], v[118:119] op_sel_hi:[1,0,1]
	v_pk_fma_f32 v[116:117], v[144:145], s[12:13], v[116:117] op_sel_hi:[1,0,1]
	v_pk_fma_f32 v[114:115], v[132:133], s[12:13], v[114:115] op_sel_hi:[1,0,1]
	v_pk_fma_f32 v[112:113], v[148:149], s[12:13], v[112:113] op_sel_hi:[1,0,1]
	v_cvt_pk_bf16_f32 v124, v124, v125
	v_cvt_pk_bf16_f32 v125, v126, v127
	v_cvt_pk_bf16_f32 v120, v120, v121
	v_cvt_pk_bf16_f32 v121, v122, v123
	v_cvt_pk_bf16_f32 v116, v116, v117
	v_cvt_pk_bf16_f32 v117, v118, v119
	v_cvt_pk_bf16_f32 v112, v112, v113
	v_cvt_pk_bf16_f32 v113, v114, v115
	v_mov_b32_e32 v224, v124
	v_mov_b32_e32 v225, v125
	v_mov_b32_e32 v226, v120
	v_mov_b32_e32 v227, v121
	v_lshl_add_u64 v[232:233], v[176:177], 0, v[234:235]
	s_nop 0
	v_permlane16_swap_b32 v224, v226
	v_permlane16_swap_b32 v225, v227
	global_store_dwordx4 v[232:233], v[224:227], off
	v_mov_b32_e32 v228, v116
	v_mov_b32_e32 v229, v117
	v_mov_b32_e32 v230, v112
	v_mov_b32_e32 v231, v113
	s_nop 1
	v_permlane16_swap_b32 v228, v230
	v_permlane16_swap_b32 v229, v231
	global_store_dwordx4 v[232:233], v[228:231], off offset:256
	global_load_dwordx2 v[114:115], v[138:139], off
	s_nop 0
	global_load_dwordx2 v[116:117], v[128:129], off offset:32
	global_load_dwordx2 v[118:119], v[128:129], off offset:256
	global_load_dwordx2 v[120:121], v[128:129], off offset:288
	s_waitcnt vmcnt(6)
	v_lshlrev_b32_e32 v126, 16, v130
	v_and_b32_e32 v127, 0xffff0000, v130
	v_lshlrev_b32_e32 v130, 16, v131
	v_and_b32_e32 v131, 0xffff0000, v131
	v_add_u32_e32 v112, 0x80, v172
	v_ashrrev_i32_e32 v113, 31, v112
	v_lshl_add_u64 v[122:123], v[112:113], 3, s[4:5]
	v_lshlrev_b64 v[112:113], 11, v[112:113]
	v_lshl_add_u64 v[112:113], s[88:89], 0, v[112:113]
	v_lshl_add_u64 v[112:113], v[112:113], 0, v[174:175]
	global_load_dwordx2 v[124:125], v[112:113], off offset:288
	s_waitcnt vmcnt(4)
	v_pk_mul_f32 v[114:115], v[114:115], s[10:11] op_sel_hi:[1,0]
	s_nop 0
	v_fma_f32 v115, -v114, v114, v115
	v_max_f32_e32 v115, 0, v115
	s_waitcnt vmcnt(2)
	v_lshlrev_b32_e32 v136, 16, v118
	v_add_f32_e32 v115, 0x3727c5ac, v115
	v_and_b32_e32 v137, 0xffff0000, v118
	v_sub_f32_e32 v118, v130, v114
	v_sub_f32_e32 v130, v136, v114
	v_rsq_f32_e32 v136, v115
	v_lshlrev_b32_e32 v132, 16, v116
	v_and_b32_e32 v133, 0xffff0000, v116
	v_lshlrev_b32_e32 v134, 16, v117
	v_and_b32_e32 v135, 0xffff0000, v117
	v_lshlrev_b32_e32 v138, 16, v119
	v_and_b32_e32 v139, 0xffff0000, v119
	s_waitcnt vmcnt(1)
	v_lshlrev_b32_e32 v140, 16, v120
	v_and_b32_e32 v141, 0xffff0000, v120
	v_lshlrev_b32_e32 v142, 16, v121
	v_and_b32_e32 v143, 0xffff0000, v121
	v_sub_f32_e32 v117, v127, v114
	v_sub_f32_e32 v116, v126, v114
	v_sub_f32_e32 v119, v131, v114
	v_sub_f32_e32 v121, v133, v114
	v_sub_f32_e32 v120, v132, v114
	v_sub_f32_e32 v127, v135, v114
	v_sub_f32_e32 v126, v134, v114
	v_sub_f32_e32 v131, v137, v114
	v_sub_f32_e32 v133, v139, v114
	v_sub_f32_e32 v132, v138, v114
	v_sub_f32_e32 v135, v141, v114
	v_sub_f32_e32 v134, v140, v114
	v_sub_f32_e32 v115, v143, v114
	v_sub_f32_e32 v114, v142, v114
	v_pk_mul_f32 v[118:119], v[136:137], v[118:119] op_sel_hi:[0,1]
	v_pk_mul_f32 v[116:117], v[136:137], v[116:117] op_sel_hi:[0,1]
	v_pk_mul_f32 v[126:127], v[136:137], v[126:127] op_sel_hi:[0,1]
	v_pk_mul_f32 v[120:121], v[136:137], v[120:121] op_sel_hi:[0,1]
	v_pk_mul_f32 v[132:133], v[136:137], v[132:133] op_sel_hi:[0,1]
	v_pk_mul_f32 v[130:131], v[136:137], v[130:131] op_sel_hi:[0,1]
	v_pk_mul_f32 v[114:115], v[136:137], v[114:115] op_sel_hi:[0,1]
	v_pk_mul_f32 v[134:135], v[136:137], v[134:135] op_sel_hi:[0,1]
	v_pk_fma_f32 v[116:117], v[96:97], v[116:117], v[80:81]
	v_pk_fma_f32 v[118:119], v[98:99], v[118:119], v[82:83]
	v_pk_fma_f32 v[120:121], v[84:85], v[120:121], v[100:101]
	v_pk_fma_f32 v[126:127], v[86:87], v[126:127], v[102:103]
	v_pk_fma_f32 v[130:131], v[104:105], v[130:131], v[88:89]
	v_pk_fma_f32 v[132:133], v[106:107], v[132:133], v[90:91]
	v_pk_fma_f32 v[134:135], v[92:93], v[134:135], v[108:109]
	v_pk_fma_f32 v[114:115], v[94:95], v[114:115], v[110:111]
	v_pk_fma_f32 v[78:79], v[118:119], s[12:13], v[78:79] op_sel_hi:[1,0,1]
	v_pk_fma_f32 v[76:77], v[116:117], s[12:13], v[76:77] op_sel_hi:[1,0,1]
	v_pk_fma_f32 v[74:75], v[126:127], s[12:13], v[74:75] op_sel_hi:[1,0,1]
	v_pk_fma_f32 v[72:73], v[120:121], s[12:13], v[72:73] op_sel_hi:[1,0,1]
	v_pk_fma_f32 v[70:71], v[132:133], s[12:13], v[70:71] op_sel_hi:[1,0,1]
	v_pk_fma_f32 v[68:69], v[130:131], s[12:13], v[68:69] op_sel_hi:[1,0,1]
	v_pk_fma_f32 v[66:67], v[114:115], s[12:13], v[66:67] op_sel_hi:[1,0,1]
	v_pk_fma_f32 v[64:65], v[134:135], s[12:13], v[64:65] op_sel_hi:[1,0,1]
	v_cvt_pk_bf16_f32 v76, v76, v77
	v_cvt_pk_bf16_f32 v77, v78, v79
	v_cvt_pk_bf16_f32 v72, v72, v73
	v_cvt_pk_bf16_f32 v73, v74, v75
	v_cvt_pk_bf16_f32 v68, v68, v69
	v_cvt_pk_bf16_f32 v69, v70, v71
	v_cvt_pk_bf16_f32 v64, v64, v65
	v_cvt_pk_bf16_f32 v65, v66, v67
	v_mov_b32_e32 v224, v76
	v_mov_b32_e32 v225, v77
	v_mov_b32_e32 v226, v72
	v_mov_b32_e32 v227, v73
	v_lshl_add_u64 v[232:233], v[128:129], 0, v[234:235]
	s_nop 0
	v_permlane16_swap_b32 v224, v226
	v_permlane16_swap_b32 v225, v227
	global_store_dwordx4 v[232:233], v[224:227], off
	v_mov_b32_e32 v228, v68
	v_mov_b32_e32 v229, v69
	v_mov_b32_e32 v230, v64
	v_mov_b32_e32 v231, v65
	s_nop 1
	v_permlane16_swap_b32 v228, v230
	v_permlane16_swap_b32 v229, v231
	global_store_dwordx4 v[232:233], v[228:231], off offset:256
	global_load_dwordx2 v[68:69], v[122:123], off
	s_nop 0
	global_load_dwordx2 v[70:71], v[112:113], off
	global_load_dwordx2 v[72:73], v[112:113], off offset:32
	global_load_dwordx2 v[74:75], v[112:113], off offset:256
	s_waitcnt vmcnt(6)
	v_lshlrev_b32_e32 v126, 16, v124
	v_and_b32_e32 v127, 0xffff0000, v124
	v_add_u32_e32 v64, 0x90, v172
	v_lshlrev_b32_e32 v129, 16, v125
	v_and_b32_e32 v130, 0xffff0000, v125
	v_add_u32_e32 v76, 0xa0, v172
	v_ashrrev_i32_e32 v65, 31, v64
	v_ashrrev_i32_e32 v77, 31, v76
	v_lshl_add_u64 v[78:79], v[64:65], 3, s[4:5]
	v_lshlrev_b64 v[64:65], 11, v[64:65]
	v_lshlrev_b64 v[66:67], 11, v[76:77]
	v_lshl_add_u64 v[64:65], s[88:89], 0, v[64:65]
	v_lshl_add_u64 v[66:67], s[88:89], 0, v[66:67]
	v_lshl_add_u64 v[114:115], v[64:65], 0, v[174:175]
	v_lshl_add_u64 v[64:65], v[66:67], 0, v[174:175]
	global_load_dwordx2 v[116:117], v[114:115], off
	global_load_dwordx2 v[118:119], v[114:115], off offset:256
	global_load_dwordx2 v[66:67], v[64:65], off
	s_waitcnt vmcnt(6)
	v_pk_mul_f32 v[68:69], v[68:69], s[10:11] op_sel_hi:[1,0]
	s_nop 0
	v_fma_f32 v69, -v68, v68, v69
	v_max_f32_e32 v69, 0, v69
	s_waitcnt vmcnt(5)
	v_lshlrev_b32_e32 v121, 16, v71
	s_waitcnt vmcnt(4)
	v_and_b32_e32 v128, 0xffff0000, v73
	v_add_f32_e32 v69, 0x3727c5ac, v69
	v_lshlrev_b32_e32 v123, 16, v72
	v_and_b32_e32 v124, 0xffff0000, v72
	v_sub_f32_e32 v72, v121, v68
	v_sub_f32_e32 v121, v128, v68
	v_rsq_f32_e32 v128, v69
	v_lshlrev_b32_e32 v120, 16, v70
	v_and_b32_e32 v70, 0xffff0000, v70
	v_and_b32_e32 v122, 0xffff0000, v71
	v_lshlrev_b32_e32 v125, 16, v73
	s_waitcnt vmcnt(3)
	v_lshlrev_b32_e32 v131, 16, v74
	v_and_b32_e32 v132, 0xffff0000, v74
	v_lshlrev_b32_e32 v133, 16, v75
	v_and_b32_e32 v134, 0xffff0000, v75
	v_sub_f32_e32 v71, v70, v68
	v_sub_f32_e32 v70, v120, v68
	v_sub_f32_e32 v73, v122, v68
	v_sub_f32_e32 v75, v124, v68
	v_sub_f32_e32 v74, v123, v68
	v_sub_f32_e32 v120, v125, v68
	v_sub_f32_e32 v123, v132, v68
	v_sub_f32_e32 v122, v131, v68
	v_sub_f32_e32 v125, v134, v68
	v_sub_f32_e32 v124, v133, v68
	v_sub_f32_e32 v127, v127, v68
	v_sub_f32_e32 v126, v126, v68
	v_sub_f32_e32 v69, v130, v68
	v_sub_f32_e32 v68, v129, v68
	v_pk_mul_f32 v[72:73], v[128:129], v[72:73] op_sel_hi:[0,1]
	v_pk_mul_f32 v[70:71], v[128:129], v[70:71] op_sel_hi:[0,1]
	v_pk_mul_f32 v[120:121], v[128:129], v[120:121] op_sel_hi:[0,1]
	v_pk_mul_f32 v[74:75], v[128:129], v[74:75] op_sel_hi:[0,1]
	v_pk_mul_f32 v[124:125], v[128:129], v[124:125] op_sel_hi:[0,1]
	v_pk_mul_f32 v[122:123], v[128:129], v[122:123] op_sel_hi:[0,1]
	v_pk_mul_f32 v[68:69], v[128:129], v[68:69] op_sel_hi:[0,1]
	v_pk_mul_f32 v[126:127], v[128:129], v[126:127] op_sel_hi:[0,1]
	v_pk_fma_f32 v[70:71], v[96:97], v[70:71], v[80:81]
	v_pk_fma_f32 v[72:73], v[98:99], v[72:73], v[82:83]
	v_pk_fma_f32 v[74:75], v[84:85], v[74:75], v[100:101]
	v_pk_fma_f32 v[120:121], v[86:87], v[120:121], v[102:103]
	v_pk_fma_f32 v[122:123], v[104:105], v[122:123], v[88:89]
	v_pk_fma_f32 v[124:125], v[106:107], v[124:125], v[90:91]
	v_pk_fma_f32 v[126:127], v[92:93], v[126:127], v[108:109]
	v_pk_fma_f32 v[68:69], v[94:95], v[68:69], v[110:111]
	v_pk_fma_f32 v[62:63], v[72:73], s[12:13], v[62:63] op_sel_hi:[1,0,1]
	v_pk_fma_f32 v[60:61], v[70:71], s[12:13], v[60:61] op_sel_hi:[1,0,1]
	v_pk_fma_f32 v[58:59], v[120:121], s[12:13], v[58:59] op_sel_hi:[1,0,1]
	v_pk_fma_f32 v[56:57], v[74:75], s[12:13], v[56:57] op_sel_hi:[1,0,1]
	v_pk_fma_f32 v[54:55], v[124:125], s[12:13], v[54:55] op_sel_hi:[1,0,1]
	v_pk_fma_f32 v[52:53], v[122:123], s[12:13], v[52:53] op_sel_hi:[1,0,1]
	v_pk_fma_f32 v[50:51], v[68:69], s[12:13], v[50:51] op_sel_hi:[1,0,1]
	v_pk_fma_f32 v[48:49], v[126:127], s[12:13], v[48:49] op_sel_hi:[1,0,1]
	v_cvt_pk_bf16_f32 v60, v60, v61
	v_cvt_pk_bf16_f32 v61, v62, v63
	v_cvt_pk_bf16_f32 v56, v56, v57
	v_cvt_pk_bf16_f32 v57, v58, v59
	v_cvt_pk_bf16_f32 v52, v52, v53
	v_cvt_pk_bf16_f32 v53, v54, v55
	v_cvt_pk_bf16_f32 v48, v48, v49
	v_cvt_pk_bf16_f32 v49, v50, v51
	v_mov_b32_e32 v224, v60
	v_mov_b32_e32 v225, v61
	v_mov_b32_e32 v226, v56
	v_mov_b32_e32 v227, v57
	v_lshl_add_u64 v[232:233], v[112:113], 0, v[234:235]
	s_nop 0
	v_permlane16_swap_b32 v224, v226
	v_permlane16_swap_b32 v225, v227
	global_store_dwordx4 v[232:233], v[224:227], off
	v_mov_b32_e32 v228, v52
	v_mov_b32_e32 v229, v53
	v_mov_b32_e32 v230, v48
	v_mov_b32_e32 v231, v49
	s_nop 1
	v_permlane16_swap_b32 v228, v230
	v_permlane16_swap_b32 v229, v231
	global_store_dwordx4 v[232:233], v[228:231], off offset:256
	global_load_dwordx2 v[48:49], v[78:79], off
	s_nop 0
	global_load_dwordx2 v[50:51], v[114:115], off offset:32
	global_load_dwordx2 v[52:53], v[114:115], off offset:288
	s_waitcnt vmcnt(7)
	v_lshlrev_b32_e32 v60, 16, v117
	v_lshlrev_b32_e32 v58, 16, v116
	v_and_b32_e32 v59, 0xffff0000, v116
	v_and_b32_e32 v61, 0xffff0000, v117
	v_lshl_add_u64 v[54:55], v[76:77], 3, s[4:5]
	s_waitcnt vmcnt(6)
	v_lshlrev_b32_e32 v62, 16, v118
	v_and_b32_e32 v63, 0xffff0000, v118
	v_lshlrev_b32_e32 v68, 16, v119
	v_and_b32_e32 v69, 0xffff0000, v119
	global_load_dwordx2 v[56:57], v[64:65], off offset:32
	s_waitcnt vmcnt(3)
	v_pk_mul_f32 v[48:49], v[48:49], s[10:11] op_sel_hi:[1,0]
	s_nop 0
	v_fma_f32 v49, -v48, v48, v49
	v_max_f32_e32 v49, 0, v49
	s_waitcnt vmcnt(2)
	v_lshlrev_b32_e32 v72, 16, v51
	v_add_f32_e32 v49, 0x3727c5ac, v49
	s_waitcnt vmcnt(1)
	v_lshlrev_b32_e32 v74, 16, v52
	v_and_b32_e32 v75, 0xffff0000, v52
	v_sub_f32_e32 v52, v60, v48
	v_sub_f32_e32 v60, v72, v48
	v_rsq_f32_e32 v72, v49
	v_lshlrev_b32_e32 v70, 16, v50
	v_and_b32_e32 v71, 0xffff0000, v50
	v_and_b32_e32 v73, 0xffff0000, v51
	v_lshlrev_b32_e32 v76, 16, v53
	v_and_b32_e32 v77, 0xffff0000, v53
	v_sub_f32_e32 v51, v59, v48
	v_sub_f32_e32 v50, v58, v48
	v_sub_f32_e32 v53, v61, v48
	v_sub_f32_e32 v59, v71, v48
	v_sub_f32_e32 v58, v70, v48
	v_sub_f32_e32 v61, v73, v48
	v_sub_f32_e32 v63, v63, v48
	v_sub_f32_e32 v62, v62, v48
	v_sub_f32_e32 v69, v69, v48
	v_sub_f32_e32 v68, v68, v48
	v_sub_f32_e32 v71, v75, v48
	v_sub_f32_e32 v70, v74, v48
	v_sub_f32_e32 v49, v77, v48
	v_sub_f32_e32 v48, v76, v48
	v_pk_mul_f32 v[52:53], v[72:73], v[52:53] op_sel_hi:[0,1]
	v_pk_mul_f32 v[50:51], v[72:73], v[50:51] op_sel_hi:[0,1]
	v_pk_mul_f32 v[60:61], v[72:73], v[60:61] op_sel_hi:[0,1]
	v_pk_mul_f32 v[58:59], v[72:73], v[58:59] op_sel_hi:[0,1]
	v_pk_mul_f32 v[68:69], v[72:73], v[68:69] op_sel_hi:[0,1]
	v_pk_mul_f32 v[62:63], v[72:73], v[62:63] op_sel_hi:[0,1]
	v_pk_mul_f32 v[48:49], v[72:73], v[48:49] op_sel_hi:[0,1]
	v_pk_mul_f32 v[70:71], v[72:73], v[70:71] op_sel_hi:[0,1]
	v_pk_fma_f32 v[50:51], v[96:97], v[50:51], v[80:81]
	v_pk_fma_f32 v[52:53], v[98:99], v[52:53], v[82:83]
	v_pk_fma_f32 v[58:59], v[84:85], v[58:59], v[100:101]
	v_pk_fma_f32 v[60:61], v[86:87], v[60:61], v[102:103]
	v_pk_fma_f32 v[62:63], v[104:105], v[62:63], v[88:89]
	v_pk_fma_f32 v[68:69], v[106:107], v[68:69], v[90:91]
	v_pk_fma_f32 v[70:71], v[92:93], v[70:71], v[108:109]
	v_pk_fma_f32 v[48:49], v[94:95], v[48:49], v[110:111]
	v_pk_fma_f32 v[46:47], v[52:53], s[12:13], v[46:47] op_sel_hi:[1,0,1]
	v_pk_fma_f32 v[44:45], v[50:51], s[12:13], v[44:45] op_sel_hi:[1,0,1]
	v_pk_fma_f32 v[42:43], v[60:61], s[12:13], v[42:43] op_sel_hi:[1,0,1]
	v_pk_fma_f32 v[40:41], v[58:59], s[12:13], v[40:41] op_sel_hi:[1,0,1]
	v_pk_fma_f32 v[38:39], v[68:69], s[12:13], v[38:39] op_sel_hi:[1,0,1]
	v_pk_fma_f32 v[36:37], v[62:63], s[12:13], v[36:37] op_sel_hi:[1,0,1]
	v_pk_fma_f32 v[34:35], v[48:49], s[12:13], v[34:35] op_sel_hi:[1,0,1]
	v_pk_fma_f32 v[32:33], v[70:71], s[12:13], v[32:33] op_sel_hi:[1,0,1]
	v_cvt_pk_bf16_f32 v44, v44, v45
	v_cvt_pk_bf16_f32 v45, v46, v47
	v_cvt_pk_bf16_f32 v40, v40, v41
	v_cvt_pk_bf16_f32 v41, v42, v43
	v_cvt_pk_bf16_f32 v36, v36, v37
	v_cvt_pk_bf16_f32 v37, v38, v39
	v_cvt_pk_bf16_f32 v32, v32, v33
	v_cvt_pk_bf16_f32 v33, v34, v35
	v_mov_b32_e32 v224, v44
	v_mov_b32_e32 v225, v45
	v_mov_b32_e32 v226, v40
	v_mov_b32_e32 v227, v41
	v_lshl_add_u64 v[232:233], v[114:115], 0, v[234:235]
	s_nop 0
	v_permlane16_swap_b32 v224, v226
	v_permlane16_swap_b32 v225, v227
	global_store_dwordx4 v[232:233], v[224:227], off
	v_mov_b32_e32 v228, v36
	v_mov_b32_e32 v229, v37
	v_mov_b32_e32 v230, v32
	v_mov_b32_e32 v231, v33
	s_nop 1
	v_permlane16_swap_b32 v228, v230
	v_permlane16_swap_b32 v229, v231
	global_store_dwordx4 v[232:233], v[228:231], off offset:256
	global_load_dwordx2 v[34:35], v[54:55], off
	s_nop 0
	global_load_dwordx2 v[36:37], v[64:65], off offset:256
	global_load_dwordx2 v[38:39], v[64:65], off offset:288
	v_lshlrev_b32_e32 v46, 16, v67
	s_waitcnt vmcnt(5)
	v_lshlrev_b32_e32 v50, 16, v57
	v_lshlrev_b32_e32 v48, 16, v56
	v_and_b32_e32 v49, 0xffff0000, v56
	v_and_b32_e32 v51, 0xffff0000, v57
	v_lshlrev_b32_e32 v44, 16, v66
	v_and_b32_e32 v45, 0xffff0000, v66
	v_and_b32_e32 v47, 0xffff0000, v67
	v_add_u32_e32 v32, 0xb0, v172
	v_ashrrev_i32_e32 v33, 31, v32
	v_lshl_add_u64 v[40:41], v[32:33], 3, s[4:5]
	v_lshlrev_b64 v[32:33], 11, v[32:33]
	v_lshl_add_u64 v[32:33], s[88:89], 0, v[32:33]
	v_lshl_add_u64 v[32:33], v[32:33], 0, v[174:175]
	global_load_dwordx2 v[42:43], v[32:33], off
	s_waitcnt vmcnt(3)
	v_pk_mul_f32 v[34:35], v[34:35], s[10:11] op_sel_hi:[1,0]
	s_nop 0
	v_fma_f32 v35, -v34, v34, v35
	v_max_f32_e32 v35, 0, v35
	s_waitcnt vmcnt(2)
	v_lshlrev_b32_e32 v54, 16, v37
	v_add_f32_e32 v35, 0x3727c5ac, v35
	s_waitcnt vmcnt(1)
	v_lshlrev_b32_e32 v56, 16, v38
	v_and_b32_e32 v57, 0xffff0000, v38
	v_sub_f32_e32 v38, v46, v34
	v_sub_f32_e32 v46, v50, v34
	v_sub_f32_e32 v50, v54, v34
	v_rsq_f32_e32 v54, v35
	v_lshlrev_b32_e32 v52, 16, v36
	v_and_b32_e32 v53, 0xffff0000, v36
	v_and_b32_e32 v55, 0xffff0000, v37
	v_lshlrev_b32_e32 v58, 16, v39
	v_and_b32_e32 v59, 0xffff0000, v39
	v_sub_f32_e32 v37, v45, v34
	v_sub_f32_e32 v36, v44, v34
	v_sub_f32_e32 v39, v47, v34
	v_sub_f32_e32 v45, v49, v34
	v_sub_f32_e32 v44, v48, v34
	v_sub_f32_e32 v47, v51, v34
	v_sub_f32_e32 v49, v53, v34
	v_sub_f32_e32 v48, v52, v34
	v_sub_f32_e32 v51, v55, v34
	v_sub_f32_e32 v53, v57, v34
	v_sub_f32_e32 v52, v56, v34
	v_sub_f32_e32 v35, v59, v34
	v_sub_f32_e32 v34, v58, v34
	v_pk_mul_f32 v[38:39], v[54:55], v[38:39] op_sel_hi:[0,1]
	v_pk_mul_f32 v[36:37], v[54:55], v[36:37] op_sel_hi:[0,1]
	v_pk_mul_f32 v[46:47], v[54:55], v[46:47] op_sel_hi:[0,1]
	v_pk_mul_f32 v[44:45], v[54:55], v[44:45] op_sel_hi:[0,1]
	v_pk_mul_f32 v[50:51], v[54:55], v[50:51] op_sel_hi:[0,1]
	v_pk_mul_f32 v[48:49], v[54:55], v[48:49] op_sel_hi:[0,1]
	v_pk_mul_f32 v[34:35], v[54:55], v[34:35] op_sel_hi:[0,1]
	v_pk_mul_f32 v[52:53], v[54:55], v[52:53] op_sel_hi:[0,1]
	v_pk_fma_f32 v[36:37], v[96:97], v[36:37], v[80:81]
	v_pk_fma_f32 v[38:39], v[98:99], v[38:39], v[82:83]
	v_pk_fma_f32 v[44:45], v[84:85], v[44:45], v[100:101]
	v_pk_fma_f32 v[46:47], v[86:87], v[46:47], v[102:103]
	v_pk_fma_f32 v[48:49], v[104:105], v[48:49], v[88:89]
	v_pk_fma_f32 v[50:51], v[106:107], v[50:51], v[90:91]
	v_pk_fma_f32 v[52:53], v[92:93], v[52:53], v[108:109]
	v_pk_fma_f32 v[34:35], v[94:95], v[34:35], v[110:111]
	v_pk_fma_f32 v[30:31], v[38:39], s[12:13], v[30:31] op_sel_hi:[1,0,1]
	v_pk_fma_f32 v[28:29], v[36:37], s[12:13], v[28:29] op_sel_hi:[1,0,1]
	v_pk_fma_f32 v[26:27], v[46:47], s[12:13], v[26:27] op_sel_hi:[1,0,1]
	v_pk_fma_f32 v[24:25], v[44:45], s[12:13], v[24:25] op_sel_hi:[1,0,1]
	v_pk_fma_f32 v[22:23], v[50:51], s[12:13], v[22:23] op_sel_hi:[1,0,1]
	v_pk_fma_f32 v[20:21], v[48:49], s[12:13], v[20:21] op_sel_hi:[1,0,1]
	v_pk_fma_f32 v[18:19], v[34:35], s[12:13], v[18:19] op_sel_hi:[1,0,1]
	v_pk_fma_f32 v[16:17], v[52:53], s[12:13], v[16:17] op_sel_hi:[1,0,1]
	v_cvt_pk_bf16_f32 v28, v28, v29
	v_cvt_pk_bf16_f32 v29, v30, v31
	v_cvt_pk_bf16_f32 v24, v24, v25
	v_cvt_pk_bf16_f32 v25, v26, v27
	v_cvt_pk_bf16_f32 v20, v20, v21
	v_cvt_pk_bf16_f32 v21, v22, v23
	v_cvt_pk_bf16_f32 v16, v16, v17
	v_cvt_pk_bf16_f32 v17, v18, v19
	v_mov_b32_e32 v224, v28
	v_mov_b32_e32 v225, v29
	v_mov_b32_e32 v226, v24
	v_mov_b32_e32 v227, v25
	v_lshl_add_u64 v[232:233], v[64:65], 0, v[234:235]
	s_nop 0
	v_permlane16_swap_b32 v224, v226
	v_permlane16_swap_b32 v225, v227
	global_store_dwordx4 v[232:233], v[224:227], off
	v_mov_b32_e32 v228, v20
	v_mov_b32_e32 v229, v21
	v_mov_b32_e32 v230, v16
	v_mov_b32_e32 v231, v17
	s_nop 1
	v_permlane16_swap_b32 v228, v230
	v_permlane16_swap_b32 v229, v231
	global_store_dwordx4 v[232:233], v[228:231], off offset:256
	global_load_dwordx2 v[16:17], v[40:41], off
	s_nop 0
	global_load_dwordx2 v[18:19], v[32:33], off offset:32
	global_load_dwordx2 v[20:21], v[32:33], off offset:256
	global_load_dwordx2 v[22:23], v[32:33], off offset:288
	s_waitcnt vmcnt(6)
	v_lshlrev_b32_e32 v26, 16, v43
	v_lshlrev_b32_e32 v24, 16, v42
	v_and_b32_e32 v25, 0xffff0000, v42
	v_and_b32_e32 v27, 0xffff0000, v43
	s_waitcnt vmcnt(3)
	v_pk_mul_f32 v[16:17], v[16:17], s[10:11] op_sel_hi:[1,0]
	s_nop 0
	v_fma_f32 v17, -v16, v16, v17
	v_max_f32_e32 v17, 0, v17
	s_waitcnt vmcnt(1)
	v_lshlrev_b32_e32 v34, 16, v20
	v_add_f32_e32 v17, 0x3727c5ac, v17
	v_and_b32_e32 v35, 0xffff0000, v20
	v_sub_f32_e32 v20, v26, v16
	v_sub_f32_e32 v26, v34, v16
	v_rsq_f32_e32 v34, v17
	v_lshlrev_b32_e32 v28, 16, v18
	v_and_b32_e32 v29, 0xffff0000, v18
	v_lshlrev_b32_e32 v30, 16, v19
	v_and_b32_e32 v31, 0xffff0000, v19
	v_lshlrev_b32_e32 v36, 16, v21
	v_and_b32_e32 v37, 0xffff0000, v21
	s_waitcnt vmcnt(0)
	v_lshlrev_b32_e32 v38, 16, v22
	v_and_b32_e32 v39, 0xffff0000, v22
	v_lshlrev_b32_e32 v40, 16, v23
	v_and_b32_e32 v41, 0xffff0000, v23
	v_sub_f32_e32 v19, v25, v16
	v_sub_f32_e32 v18, v24, v16
	v_sub_f32_e32 v21, v27, v16
	v_sub_f32_e32 v23, v29, v16
	v_sub_f32_e32 v22, v28, v16
	v_sub_f32_e32 v25, v31, v16
	v_sub_f32_e32 v24, v30, v16
	v_sub_f32_e32 v27, v35, v16
	v_sub_f32_e32 v29, v37, v16
	v_sub_f32_e32 v28, v36, v16
	v_sub_f32_e32 v31, v39, v16
	v_sub_f32_e32 v30, v38, v16
	v_sub_f32_e32 v17, v41, v16
	v_sub_f32_e32 v16, v40, v16
	v_pk_mul_f32 v[20:21], v[34:35], v[20:21] op_sel_hi:[0,1]
	v_pk_mul_f32 v[18:19], v[34:35], v[18:19] op_sel_hi:[0,1]
	v_pk_mul_f32 v[24:25], v[34:35], v[24:25] op_sel_hi:[0,1]
	v_pk_mul_f32 v[22:23], v[34:35], v[22:23] op_sel_hi:[0,1]
	v_pk_mul_f32 v[28:29], v[34:35], v[28:29] op_sel_hi:[0,1]
	v_pk_mul_f32 v[26:27], v[34:35], v[26:27] op_sel_hi:[0,1]
	v_pk_mul_f32 v[16:17], v[34:35], v[16:17] op_sel_hi:[0,1]
	v_pk_mul_f32 v[30:31], v[34:35], v[30:31] op_sel_hi:[0,1]
	v_pk_fma_f32 v[18:19], v[96:97], v[18:19], v[80:81]
	v_pk_fma_f32 v[20:21], v[98:99], v[20:21], v[82:83]
	v_pk_fma_f32 v[22:23], v[84:85], v[22:23], v[100:101]
	v_pk_fma_f32 v[24:25], v[86:87], v[24:25], v[102:103]
	v_pk_fma_f32 v[26:27], v[104:105], v[26:27], v[88:89]
	v_pk_fma_f32 v[28:29], v[106:107], v[28:29], v[90:91]
	v_pk_fma_f32 v[30:31], v[92:93], v[30:31], v[108:109]
	v_pk_fma_f32 v[16:17], v[94:95], v[16:17], v[110:111]
	v_pk_fma_f32 v[14:15], v[20:21], s[12:13], v[14:15] op_sel_hi:[1,0,1]
	v_pk_fma_f32 v[12:13], v[18:19], s[12:13], v[12:13] op_sel_hi:[1,0,1]
	v_pk_fma_f32 v[10:11], v[24:25], s[12:13], v[10:11] op_sel_hi:[1,0,1]
	v_pk_fma_f32 v[8:9], v[22:23], s[12:13], v[8:9] op_sel_hi:[1,0,1]
	v_pk_fma_f32 v[6:7], v[28:29], s[12:13], v[6:7] op_sel_hi:[1,0,1]
	v_pk_fma_f32 v[4:5], v[26:27], s[12:13], v[4:5] op_sel_hi:[1,0,1]
	v_pk_fma_f32 v[2:3], v[16:17], s[12:13], v[2:3] op_sel_hi:[1,0,1]
	v_pk_fma_f32 v[0:1], v[30:31], s[12:13], v[0:1] op_sel_hi:[1,0,1]
	v_cvt_pk_bf16_f32 v12, v12, v13
	v_cvt_pk_bf16_f32 v13, v14, v15
	v_cvt_pk_bf16_f32 v8, v8, v9
	v_cvt_pk_bf16_f32 v9, v10, v11
	v_cvt_pk_bf16_f32 v4, v4, v5
	v_cvt_pk_bf16_f32 v5, v6, v7
	v_cvt_pk_bf16_f32 v0, v0, v1
	v_cvt_pk_bf16_f32 v1, v2, v3
	v_mov_b32_e32 v224, v12
	v_mov_b32_e32 v225, v13
	v_mov_b32_e32 v226, v8
	v_mov_b32_e32 v227, v9
	v_lshl_add_u64 v[232:233], v[32:33], 0, v[234:235]
	s_nop 0
	v_permlane16_swap_b32 v224, v226
	v_permlane16_swap_b32 v225, v227
	global_store_dwordx4 v[232:233], v[224:227], off
	v_mov_b32_e32 v228, v4
	v_mov_b32_e32 v229, v5
	v_mov_b32_e32 v230, v0
	v_mov_b32_e32 v231, v1
	s_nop 1
	v_permlane16_swap_b32 v228, v230
	v_permlane16_swap_b32 v229, v231
	global_store_dwordx4 v[232:233], v[228:231], off offset:256
	s_cbranch_vccnz .LBB0_527
	s_andn2_b64 vcc, exec, s[0:1]
	s_cbranch_vccnz .LBB0_526
	s_barrier
	s_branch .LBB0_526
